# gate sigmoid computed in the in-proj gate-tile epilogue (stored as bf16 sigmoid), branch epilogue multiplies directly; stores interleaved with the sigmoid math
# speedup vs baseline: 1.0251x; 1.0048x over previous
.LBB0_244:
	s_lshl_b32 s9, s35, 3
	s_lshl_b32 s7, s36, 7
	s_add_i32 s9, s30, s9
	s_add_i32 s14, s9, s7
	s_ashr_i32 s15, s14, 31
	s_lshl_b64 s[14:15], s[14:15], 14
	v_lshl_add_u64 v[156:157], v[138:139], 0, s[14:15]
	v_mul_f32_e32 v96, 0xbfb8aa3b, v96
	v_mul_f32_e32 v97, 0xbfb8aa3b, v97
	v_exp_f32_e32 v96, v96
	v_exp_f32_e32 v97, v97
	v_add_f32_e32 v96, 1.0, v96
	v_add_f32_e32 v97, 1.0, v97
	v_rcp_f32_e32 v96, v96
	v_rcp_f32_e32 v97, v97
	s_nop 0
	v_cvt_pk_bf16_f32 v97, v96, v97
	v_mul_f32_e32 v94, 0xbfb8aa3b, v94
	v_mul_f32_e32 v95, 0xbfb8aa3b, v95
	v_exp_f32_e32 v94, v94
	v_exp_f32_e32 v95, v95
	v_add_f32_e32 v94, 1.0, v94
	v_add_f32_e32 v95, 1.0, v95
	v_rcp_f32_e32 v94, v94
	v_rcp_f32_e32 v95, v95
	s_nop 0
	v_cvt_pk_bf16_f32 v96, v94, v95
	v_mul_f32_e32 v90, 0xbfb8aa3b, v90
	v_mul_f32_e32 v91, 0xbfb8aa3b, v91
	v_exp_f32_e32 v90, v90
	v_exp_f32_e32 v91, v91
	v_add_f32_e32 v90, 1.0, v90
	v_add_f32_e32 v91, 1.0, v91
	v_rcp_f32_e32 v90, v90
	v_rcp_f32_e32 v91, v91
	s_nop 0
	v_cvt_pk_bf16_f32 v94, v90, v91
	v_add_co_u32_e32 v90, vcc, s63, v156
	s_movk_i32 s7, 0x2000
	s_nop 0
	v_addc_co_u32_e32 v91, vcc, 0, v157, vcc
	v_mul_f32_e32 v92, 0xbfb8aa3b, v92
	v_mul_f32_e32 v93, 0xbfb8aa3b, v93
	v_exp_f32_e32 v92, v92
	v_exp_f32_e32 v93, v93
	v_add_f32_e32 v92, 1.0, v92
	v_add_f32_e32 v93, 1.0, v93
	v_rcp_f32_e32 v92, v92
	v_rcp_f32_e32 v93, v93
	s_nop 0
	v_cvt_pk_bf16_f32 v95, v92, v93
	v_add_co_u32_e32 v92, vcc, s7, v156
	s_movk_i32 s7, 0x3000
	s_nop 0
	v_addc_co_u32_e32 v93, vcc, 0, v157, vcc
	v_mul_f32_e32 v32, 0xbfb8aa3b, v32
	v_mul_f32_e32 v33, 0xbfb8aa3b, v33
	v_exp_f32_e32 v32, v32
	v_exp_f32_e32 v33, v33
	v_add_f32_e32 v32, 1.0, v32
	v_add_f32_e32 v33, 1.0, v33
	v_rcp_f32_e32 v32, v32
	v_rcp_f32_e32 v33, v33
	s_nop 0
	v_cvt_pk_bf16_f32 v33, v32, v33
	v_mul_f32_e32 v30, 0xbfb8aa3b, v30
	v_mul_f32_e32 v31, 0xbfb8aa3b, v31
	v_exp_f32_e32 v30, v30
	v_exp_f32_e32 v31, v31
	v_add_f32_e32 v30, 1.0, v30
	v_add_f32_e32 v31, 1.0, v31
	v_rcp_f32_e32 v30, v30
	v_rcp_f32_e32 v31, v31
	s_nop 0
	v_cvt_pk_bf16_f32 v32, v30, v31
	v_mul_f32_e32 v26, 0xbfb8aa3b, v26
	v_mul_f32_e32 v27, 0xbfb8aa3b, v27
	v_exp_f32_e32 v26, v26
	v_exp_f32_e32 v27, v27
	v_add_f32_e32 v26, 1.0, v26
	v_add_f32_e32 v27, 1.0, v27
	v_rcp_f32_e32 v26, v26
	v_rcp_f32_e32 v27, v27
	s_nop 0
	v_cvt_pk_bf16_f32 v30, v26, v27
	v_add_co_u32_e32 v26, vcc, s7, v156
	v_mul_f32_e32 v128, 0xbfb8aa3b, v128
	v_mul_f32_e32 v129, 0xbfb8aa3b, v129
	v_exp_f32_e32 v128, v128
	v_exp_f32_e32 v129, v129
	v_add_f32_e32 v128, 1.0, v128
	v_add_f32_e32 v129, 1.0, v129
	v_rcp_f32_e32 v128, v128
	v_rcp_f32_e32 v129, v129
	s_nop 0
	v_cvt_pk_bf16_f32 v129, v128, v129
	v_mul_f32_e32 v126, 0xbfb8aa3b, v126
	v_mul_f32_e32 v127, 0xbfb8aa3b, v127
	v_exp_f32_e32 v126, v126
	v_exp_f32_e32 v127, v127
	v_add_f32_e32 v126, 1.0, v126
	v_add_f32_e32 v127, 1.0, v127
	v_rcp_f32_e32 v126, v126
	v_rcp_f32_e32 v127, v127
	s_nop 0
	v_cvt_pk_bf16_f32 v128, v126, v127
	v_mul_f32_e32 v124, 0xbfb8aa3b, v124
	v_mul_f32_e32 v125, 0xbfb8aa3b, v125
	v_exp_f32_e32 v124, v124
	v_exp_f32_e32 v125, v125
	v_add_f32_e32 v124, 1.0, v124
	v_add_f32_e32 v125, 1.0, v125
	v_rcp_f32_e32 v124, v124
	v_rcp_f32_e32 v125, v125
	s_nop 0
	v_cvt_pk_bf16_f32 v127, v124, v125
	v_mul_f32_e32 v122, 0xbfb8aa3b, v122
	v_mul_f32_e32 v123, 0xbfb8aa3b, v123
	v_exp_f32_e32 v122, v122
	v_exp_f32_e32 v123, v123
	v_add_f32_e32 v122, 1.0, v122
	v_add_f32_e32 v123, 1.0, v123
	v_rcp_f32_e32 v122, v122
	v_rcp_f32_e32 v123, v123
	s_nop 0
	v_cvt_pk_bf16_f32 v126, v122, v123
	global_store_dwordx4 v[156:157], v[126:129], off
	v_mul_f32_e32 v120, 0xbfb8aa3b, v120
	v_mul_f32_e32 v121, 0xbfb8aa3b, v121
	v_exp_f32_e32 v120, v120
	v_exp_f32_e32 v121, v121
	v_add_f32_e32 v120, 1.0, v120
	v_add_f32_e32 v121, 1.0, v121
	v_rcp_f32_e32 v120, v120
	v_rcp_f32_e32 v121, v121
	s_nop 0
	v_cvt_pk_bf16_f32 v121, v120, v121
	v_mul_f32_e32 v118, 0xbfb8aa3b, v118
	v_mul_f32_e32 v119, 0xbfb8aa3b, v119
	v_exp_f32_e32 v118, v118
	v_exp_f32_e32 v119, v119
	v_add_f32_e32 v118, 1.0, v118
	v_add_f32_e32 v119, 1.0, v119
	v_rcp_f32_e32 v118, v118
	v_rcp_f32_e32 v119, v119
	s_nop 0
	v_cvt_pk_bf16_f32 v120, v118, v119
	v_mul_f32_e32 v116, 0xbfb8aa3b, v116
	v_mul_f32_e32 v117, 0xbfb8aa3b, v117
	v_exp_f32_e32 v116, v116
	v_exp_f32_e32 v117, v117
	v_add_f32_e32 v116, 1.0, v116
	v_add_f32_e32 v117, 1.0, v117
	v_rcp_f32_e32 v116, v116
	v_rcp_f32_e32 v117, v117
	s_nop 0
	v_cvt_pk_bf16_f32 v119, v116, v117
	v_mul_f32_e32 v114, 0xbfb8aa3b, v114
	v_mul_f32_e32 v115, 0xbfb8aa3b, v115
	v_exp_f32_e32 v114, v114
	v_exp_f32_e32 v115, v115
	v_add_f32_e32 v114, 1.0, v114
	v_add_f32_e32 v115, 1.0, v115
	v_rcp_f32_e32 v114, v114
	v_rcp_f32_e32 v115, v115
	s_nop 0
	v_cvt_pk_bf16_f32 v118, v114, v115
	global_store_dwordx4 v[156:157], v[118:121], off offset:1024
	v_mul_f32_e32 v112, 0xbfb8aa3b, v112
	v_mul_f32_e32 v113, 0xbfb8aa3b, v113
	v_exp_f32_e32 v112, v112
	v_exp_f32_e32 v113, v113
	v_add_f32_e32 v112, 1.0, v112
	v_add_f32_e32 v113, 1.0, v113
	v_rcp_f32_e32 v112, v112
	v_rcp_f32_e32 v113, v113
	s_nop 0
	v_cvt_pk_bf16_f32 v113, v112, v113
	v_mul_f32_e32 v110, 0xbfb8aa3b, v110
	v_mul_f32_e32 v111, 0xbfb8aa3b, v111
	v_exp_f32_e32 v110, v110
	v_exp_f32_e32 v111, v111
	v_add_f32_e32 v110, 1.0, v110
	v_add_f32_e32 v111, 1.0, v111
	v_rcp_f32_e32 v110, v110
	v_rcp_f32_e32 v111, v111
	s_nop 0
	v_cvt_pk_bf16_f32 v112, v110, v111
	v_mul_f32_e32 v108, 0xbfb8aa3b, v108
	v_mul_f32_e32 v109, 0xbfb8aa3b, v109
	v_exp_f32_e32 v108, v108
	v_exp_f32_e32 v109, v109
	v_add_f32_e32 v108, 1.0, v108
	v_add_f32_e32 v109, 1.0, v109
	v_rcp_f32_e32 v108, v108
	v_rcp_f32_e32 v109, v109
	s_nop 0
	v_cvt_pk_bf16_f32 v111, v108, v109
	v_mul_f32_e32 v106, 0xbfb8aa3b, v106
	v_mul_f32_e32 v107, 0xbfb8aa3b, v107
	v_exp_f32_e32 v106, v106
	v_exp_f32_e32 v107, v107
	v_add_f32_e32 v106, 1.0, v106
	v_add_f32_e32 v107, 1.0, v107
	v_rcp_f32_e32 v106, v106
	v_rcp_f32_e32 v107, v107
	s_nop 0
	v_cvt_pk_bf16_f32 v110, v106, v107
	global_store_dwordx4 v[156:157], v[110:113], off offset:2048
	v_mul_f32_e32 v104, 0xbfb8aa3b, v104
	v_mul_f32_e32 v105, 0xbfb8aa3b, v105
	v_exp_f32_e32 v104, v104
	v_exp_f32_e32 v105, v105
	v_add_f32_e32 v104, 1.0, v104
	v_add_f32_e32 v105, 1.0, v105
	v_rcp_f32_e32 v104, v104
	v_rcp_f32_e32 v105, v105
	s_nop 0
	v_cvt_pk_bf16_f32 v105, v104, v105
	v_mul_f32_e32 v102, 0xbfb8aa3b, v102
	v_mul_f32_e32 v103, 0xbfb8aa3b, v103
	v_exp_f32_e32 v102, v102
	v_exp_f32_e32 v103, v103
	v_add_f32_e32 v102, 1.0, v102
	v_add_f32_e32 v103, 1.0, v103
	v_rcp_f32_e32 v102, v102
	v_rcp_f32_e32 v103, v103
	s_nop 0
	v_cvt_pk_bf16_f32 v104, v102, v103
	v_mul_f32_e32 v100, 0xbfb8aa3b, v100
	v_mul_f32_e32 v101, 0xbfb8aa3b, v101
	v_exp_f32_e32 v100, v100
	v_exp_f32_e32 v101, v101
	v_add_f32_e32 v100, 1.0, v100
	v_add_f32_e32 v101, 1.0, v101
	v_rcp_f32_e32 v100, v100
	v_rcp_f32_e32 v101, v101
	s_nop 0
	v_cvt_pk_bf16_f32 v103, v100, v101
	v_mul_f32_e32 v98, 0xbfb8aa3b, v98
	v_mul_f32_e32 v99, 0xbfb8aa3b, v99
	v_exp_f32_e32 v98, v98
	v_exp_f32_e32 v99, v99
	v_add_f32_e32 v98, 1.0, v98
	v_add_f32_e32 v99, 1.0, v99
	v_rcp_f32_e32 v98, v98
	v_rcp_f32_e32 v99, v99
	s_nop 0
	v_cvt_pk_bf16_f32 v102, v98, v99
	global_store_dwordx4 v[156:157], v[102:105], off offset:3072
	global_store_dwordx4 v[92:93], v[94:97], off offset:-4096
	v_mul_f32_e32 v88, 0xbfb8aa3b, v88
	v_mul_f32_e32 v89, 0xbfb8aa3b, v89
	v_exp_f32_e32 v88, v88
	v_exp_f32_e32 v89, v89
	v_add_f32_e32 v88, 1.0, v88
	v_add_f32_e32 v89, 1.0, v89
	v_rcp_f32_e32 v88, v88
	v_rcp_f32_e32 v89, v89
	s_nop 0
	v_cvt_pk_bf16_f32 v89, v88, v89
	v_mul_f32_e32 v86, 0xbfb8aa3b, v86
	v_mul_f32_e32 v87, 0xbfb8aa3b, v87
	v_exp_f32_e32 v86, v86
	v_exp_f32_e32 v87, v87
	v_add_f32_e32 v86, 1.0, v86
	v_add_f32_e32 v87, 1.0, v87
	v_rcp_f32_e32 v86, v86
	v_rcp_f32_e32 v87, v87
	s_nop 0
	v_cvt_pk_bf16_f32 v88, v86, v87
	v_mul_f32_e32 v84, 0xbfb8aa3b, v84
	v_mul_f32_e32 v85, 0xbfb8aa3b, v85
	v_exp_f32_e32 v84, v84
	v_exp_f32_e32 v85, v85
	v_add_f32_e32 v84, 1.0, v84
	v_add_f32_e32 v85, 1.0, v85
	v_rcp_f32_e32 v84, v84
	v_rcp_f32_e32 v85, v85
	s_nop 0
	v_cvt_pk_bf16_f32 v87, v84, v85
	v_mul_f32_e32 v82, 0xbfb8aa3b, v82
	v_mul_f32_e32 v83, 0xbfb8aa3b, v83
	v_exp_f32_e32 v82, v82
	v_exp_f32_e32 v83, v83
	v_add_f32_e32 v82, 1.0, v82
	v_add_f32_e32 v83, 1.0, v83
	v_rcp_f32_e32 v82, v82
	v_rcp_f32_e32 v83, v83
	s_nop 0
	v_cvt_pk_bf16_f32 v86, v82, v83
	global_store_dwordx4 v[90:91], v[86:89], off offset:1024
	v_mul_f32_e32 v80, 0xbfb8aa3b, v80
	v_mul_f32_e32 v81, 0xbfb8aa3b, v81
	v_exp_f32_e32 v80, v80
	v_exp_f32_e32 v81, v81
	v_add_f32_e32 v80, 1.0, v80
	v_add_f32_e32 v81, 1.0, v81
	v_rcp_f32_e32 v80, v80
	v_rcp_f32_e32 v81, v81
	s_nop 0
	v_cvt_pk_bf16_f32 v81, v80, v81
	v_mul_f32_e32 v78, 0xbfb8aa3b, v78
	v_mul_f32_e32 v79, 0xbfb8aa3b, v79
	v_exp_f32_e32 v78, v78
	v_exp_f32_e32 v79, v79
	v_add_f32_e32 v78, 1.0, v78
	v_add_f32_e32 v79, 1.0, v79
	v_rcp_f32_e32 v78, v78
	v_rcp_f32_e32 v79, v79
	s_nop 0
	v_cvt_pk_bf16_f32 v80, v78, v79
	v_mul_f32_e32 v76, 0xbfb8aa3b, v76
	v_mul_f32_e32 v77, 0xbfb8aa3b, v77
	v_exp_f32_e32 v76, v76
	v_exp_f32_e32 v77, v77
	v_add_f32_e32 v76, 1.0, v76
	v_add_f32_e32 v77, 1.0, v77
	v_rcp_f32_e32 v76, v76
	v_rcp_f32_e32 v77, v77
	s_nop 0
	v_cvt_pk_bf16_f32 v79, v76, v77
	v_mul_f32_e32 v74, 0xbfb8aa3b, v74
	v_mul_f32_e32 v75, 0xbfb8aa3b, v75
	v_exp_f32_e32 v74, v74
	v_exp_f32_e32 v75, v75
	v_add_f32_e32 v74, 1.0, v74
	v_add_f32_e32 v75, 1.0, v75
	v_rcp_f32_e32 v74, v74
	v_rcp_f32_e32 v75, v75
	s_nop 0
	v_cvt_pk_bf16_f32 v78, v74, v75
	global_store_dwordx4 v[90:91], v[78:81], off offset:2048
	v_mul_f32_e32 v72, 0xbfb8aa3b, v72
	v_mul_f32_e32 v73, 0xbfb8aa3b, v73
	v_exp_f32_e32 v72, v72
	v_exp_f32_e32 v73, v73
	v_add_f32_e32 v72, 1.0, v72
	v_add_f32_e32 v73, 1.0, v73
	v_rcp_f32_e32 v72, v72
	v_rcp_f32_e32 v73, v73
	s_nop 0
	v_cvt_pk_bf16_f32 v73, v72, v73
	v_mul_f32_e32 v70, 0xbfb8aa3b, v70
	v_mul_f32_e32 v71, 0xbfb8aa3b, v71
	v_exp_f32_e32 v70, v70
	v_exp_f32_e32 v71, v71
	v_add_f32_e32 v70, 1.0, v70
	v_add_f32_e32 v71, 1.0, v71
	v_rcp_f32_e32 v70, v70
	v_rcp_f32_e32 v71, v71
	s_nop 0
	v_cvt_pk_bf16_f32 v72, v70, v71
	v_mul_f32_e32 v68, 0xbfb8aa3b, v68
	v_mul_f32_e32 v69, 0xbfb8aa3b, v69
	v_exp_f32_e32 v68, v68
	v_exp_f32_e32 v69, v69
	v_add_f32_e32 v68, 1.0, v68
	v_add_f32_e32 v69, 1.0, v69
	v_rcp_f32_e32 v68, v68
	v_rcp_f32_e32 v69, v69
	s_nop 0
	v_cvt_pk_bf16_f32 v71, v68, v69
	v_mul_f32_e32 v66, 0xbfb8aa3b, v66
	v_mul_f32_e32 v67, 0xbfb8aa3b, v67
	v_exp_f32_e32 v66, v66
	v_exp_f32_e32 v67, v67
	v_add_f32_e32 v66, 1.0, v66
	v_add_f32_e32 v67, 1.0, v67
	v_rcp_f32_e32 v66, v66
	v_rcp_f32_e32 v67, v67
	s_nop 0
	v_cvt_pk_bf16_f32 v70, v66, v67
	global_store_dwordx4 v[90:91], v[70:73], off offset:3072
	v_mul_f32_e32 v64, 0xbfb8aa3b, v64
	v_mul_f32_e32 v65, 0xbfb8aa3b, v65
	v_exp_f32_e32 v64, v64
	v_exp_f32_e32 v65, v65
	v_add_f32_e32 v64, 1.0, v64
	v_add_f32_e32 v65, 1.0, v65
	v_rcp_f32_e32 v64, v64
	v_rcp_f32_e32 v65, v65
	s_nop 0
	v_cvt_pk_bf16_f32 v65, v64, v65
	v_mul_f32_e32 v62, 0xbfb8aa3b, v62
	v_mul_f32_e32 v63, 0xbfb8aa3b, v63
	v_exp_f32_e32 v62, v62
	v_exp_f32_e32 v63, v63
	v_add_f32_e32 v62, 1.0, v62
	v_add_f32_e32 v63, 1.0, v63
	v_rcp_f32_e32 v62, v62
	v_rcp_f32_e32 v63, v63
	s_nop 0
	v_cvt_pk_bf16_f32 v64, v62, v63
	v_mul_f32_e32 v60, 0xbfb8aa3b, v60
	v_mul_f32_e32 v61, 0xbfb8aa3b, v61
	v_exp_f32_e32 v60, v60
	v_exp_f32_e32 v61, v61
	v_add_f32_e32 v60, 1.0, v60
	v_add_f32_e32 v61, 1.0, v61
	v_rcp_f32_e32 v60, v60
	v_rcp_f32_e32 v61, v61
	s_nop 0
	v_cvt_pk_bf16_f32 v63, v60, v61
	v_mul_f32_e32 v58, 0xbfb8aa3b, v58
	v_mul_f32_e32 v59, 0xbfb8aa3b, v59
	v_exp_f32_e32 v58, v58
	v_exp_f32_e32 v59, v59
	v_add_f32_e32 v58, 1.0, v58
	v_add_f32_e32 v59, 1.0, v59
	v_rcp_f32_e32 v58, v58
	v_rcp_f32_e32 v59, v59
	s_nop 0
	v_cvt_pk_bf16_f32 v62, v58, v59
	global_store_dwordx4 v[92:93], v[62:65], off
	v_mul_f32_e32 v56, 0xbfb8aa3b, v56
	v_mul_f32_e32 v57, 0xbfb8aa3b, v57
	v_exp_f32_e32 v56, v56
	v_exp_f32_e32 v57, v57
	v_add_f32_e32 v56, 1.0, v56
	v_add_f32_e32 v57, 1.0, v57
	v_rcp_f32_e32 v56, v56
	v_rcp_f32_e32 v57, v57
	s_nop 0
	v_cvt_pk_bf16_f32 v57, v56, v57
	v_mul_f32_e32 v54, 0xbfb8aa3b, v54
	v_mul_f32_e32 v55, 0xbfb8aa3b, v55
	v_exp_f32_e32 v54, v54
	v_exp_f32_e32 v55, v55
	v_add_f32_e32 v54, 1.0, v54
	v_add_f32_e32 v55, 1.0, v55
	v_rcp_f32_e32 v54, v54
	v_rcp_f32_e32 v55, v55
	s_nop 0
	v_cvt_pk_bf16_f32 v56, v54, v55
	v_mul_f32_e32 v52, 0xbfb8aa3b, v52
	v_mul_f32_e32 v53, 0xbfb8aa3b, v53
	v_exp_f32_e32 v52, v52
	v_exp_f32_e32 v53, v53
	v_add_f32_e32 v52, 1.0, v52
	v_add_f32_e32 v53, 1.0, v53
	v_rcp_f32_e32 v52, v52
	v_rcp_f32_e32 v53, v53
	s_nop 0
	v_cvt_pk_bf16_f32 v55, v52, v53
	v_mul_f32_e32 v50, 0xbfb8aa3b, v50
	v_mul_f32_e32 v51, 0xbfb8aa3b, v51
	v_exp_f32_e32 v50, v50
	v_exp_f32_e32 v51, v51
	v_add_f32_e32 v50, 1.0, v50
	v_add_f32_e32 v51, 1.0, v51
	v_rcp_f32_e32 v50, v50
	v_rcp_f32_e32 v51, v51
	s_nop 0
	v_cvt_pk_bf16_f32 v54, v50, v51
	global_store_dwordx4 v[92:93], v[54:57], off offset:1024
	v_mul_f32_e32 v48, 0xbfb8aa3b, v48
	v_mul_f32_e32 v49, 0xbfb8aa3b, v49
	v_exp_f32_e32 v48, v48
	v_exp_f32_e32 v49, v49
	v_add_f32_e32 v48, 1.0, v48
	v_add_f32_e32 v49, 1.0, v49
	v_rcp_f32_e32 v48, v48
	v_rcp_f32_e32 v49, v49
	s_nop 0
	v_cvt_pk_bf16_f32 v49, v48, v49
	v_mul_f32_e32 v46, 0xbfb8aa3b, v46
	v_mul_f32_e32 v47, 0xbfb8aa3b, v47
	v_exp_f32_e32 v46, v46
	v_exp_f32_e32 v47, v47
	v_add_f32_e32 v46, 1.0, v46
	v_add_f32_e32 v47, 1.0, v47
	v_rcp_f32_e32 v46, v46
	v_rcp_f32_e32 v47, v47
	s_nop 0
	v_cvt_pk_bf16_f32 v48, v46, v47
	v_mul_f32_e32 v44, 0xbfb8aa3b, v44
	v_mul_f32_e32 v45, 0xbfb8aa3b, v45
	v_exp_f32_e32 v44, v44
	v_exp_f32_e32 v45, v45
	v_add_f32_e32 v44, 1.0, v44
	v_add_f32_e32 v45, 1.0, v45
	v_rcp_f32_e32 v44, v44
	v_rcp_f32_e32 v45, v45
	s_nop 0
	v_cvt_pk_bf16_f32 v47, v44, v45
	v_mul_f32_e32 v42, 0xbfb8aa3b, v42
	v_mul_f32_e32 v43, 0xbfb8aa3b, v43
	v_exp_f32_e32 v42, v42
	v_exp_f32_e32 v43, v43
	v_add_f32_e32 v42, 1.0, v42
	v_add_f32_e32 v43, 1.0, v43
	v_rcp_f32_e32 v42, v42
	v_rcp_f32_e32 v43, v43
	s_nop 0
	v_cvt_pk_bf16_f32 v46, v42, v43
	global_store_dwordx4 v[92:93], v[46:49], off offset:2048
	v_mul_f32_e32 v40, 0xbfb8aa3b, v40
	v_mul_f32_e32 v41, 0xbfb8aa3b, v41
	v_exp_f32_e32 v40, v40
	v_exp_f32_e32 v41, v41
	v_add_f32_e32 v40, 1.0, v40
	v_add_f32_e32 v41, 1.0, v41
	v_rcp_f32_e32 v40, v40
	v_rcp_f32_e32 v41, v41
	s_nop 0
	v_cvt_pk_bf16_f32 v41, v40, v41
	v_mul_f32_e32 v38, 0xbfb8aa3b, v38
	v_mul_f32_e32 v39, 0xbfb8aa3b, v39
	v_exp_f32_e32 v38, v38
	v_exp_f32_e32 v39, v39
	v_add_f32_e32 v38, 1.0, v38
	v_add_f32_e32 v39, 1.0, v39
	v_rcp_f32_e32 v38, v38
	v_rcp_f32_e32 v39, v39
	s_nop 0
	v_cvt_pk_bf16_f32 v40, v38, v39
	v_mul_f32_e32 v36, 0xbfb8aa3b, v36
	v_mul_f32_e32 v37, 0xbfb8aa3b, v37
	v_exp_f32_e32 v36, v36
	v_exp_f32_e32 v37, v37
	v_add_f32_e32 v36, 1.0, v36
	v_add_f32_e32 v37, 1.0, v37
	v_rcp_f32_e32 v36, v36
	v_rcp_f32_e32 v37, v37
	s_nop 0
	v_cvt_pk_bf16_f32 v39, v36, v37
	v_mul_f32_e32 v34, 0xbfb8aa3b, v34
	v_mul_f32_e32 v35, 0xbfb8aa3b, v35
	v_exp_f32_e32 v34, v34
	v_exp_f32_e32 v35, v35
	v_add_f32_e32 v34, 1.0, v34
	v_add_f32_e32 v35, 1.0, v35
	v_rcp_f32_e32 v34, v34
	v_rcp_f32_e32 v35, v35
	s_nop 0
	v_cvt_pk_bf16_f32 v38, v34, v35
	global_store_dwordx4 v[92:93], v[38:41], off offset:3072
	v_mul_f32_e32 v28, 0xbfb8aa3b, v28
	v_mul_f32_e32 v29, 0xbfb8aa3b, v29
	v_exp_f32_e32 v28, v28
	v_exp_f32_e32 v29, v29
	v_add_f32_e32 v28, 1.0, v28
	v_add_f32_e32 v29, 1.0, v29
	v_rcp_f32_e32 v28, v28
	v_rcp_f32_e32 v29, v29
	s_nop 0
	v_cvt_pk_bf16_f32 v31, v28, v29
	v_addc_co_u32_e32 v27, vcc, 0, v157, vcc
	global_store_dwordx4 v[26:27], v[30:33], off
	v_mul_f32_e32 v24, 0xbfb8aa3b, v24
	v_mul_f32_e32 v25, 0xbfb8aa3b, v25
	v_exp_f32_e32 v24, v24
	v_exp_f32_e32 v25, v25
	v_add_f32_e32 v24, 1.0, v24
	v_add_f32_e32 v25, 1.0, v25
	v_rcp_f32_e32 v24, v24
	v_rcp_f32_e32 v25, v25
	s_nop 0
	v_cvt_pk_bf16_f32 v25, v24, v25
	v_mul_f32_e32 v22, 0xbfb8aa3b, v22
	v_mul_f32_e32 v23, 0xbfb8aa3b, v23
	v_exp_f32_e32 v22, v22
	v_exp_f32_e32 v23, v23
	v_add_f32_e32 v22, 1.0, v22
	v_add_f32_e32 v23, 1.0, v23
	v_rcp_f32_e32 v22, v22
	v_rcp_f32_e32 v23, v23
	s_nop 0
	v_cvt_pk_bf16_f32 v24, v22, v23
	v_mul_f32_e32 v20, 0xbfb8aa3b, v20
	v_mul_f32_e32 v21, 0xbfb8aa3b, v21
	v_exp_f32_e32 v20, v20
	v_exp_f32_e32 v21, v21
	v_add_f32_e32 v20, 1.0, v20
	v_add_f32_e32 v21, 1.0, v21
	v_rcp_f32_e32 v20, v20
	v_rcp_f32_e32 v21, v21
	s_nop 0
	v_cvt_pk_bf16_f32 v23, v20, v21
	v_mul_f32_e32 v18, 0xbfb8aa3b, v18
	v_mul_f32_e32 v19, 0xbfb8aa3b, v19
	v_exp_f32_e32 v18, v18
	v_exp_f32_e32 v19, v19
	v_add_f32_e32 v18, 1.0, v18
	v_add_f32_e32 v19, 1.0, v19
	v_rcp_f32_e32 v18, v18
	v_rcp_f32_e32 v19, v19
	s_nop 0
	v_cvt_pk_bf16_f32 v22, v18, v19
	global_store_dwordx4 v[26:27], v[22:25], off offset:1024
	v_mul_f32_e32 v16, 0xbfb8aa3b, v16
	v_mul_f32_e32 v17, 0xbfb8aa3b, v17
	v_exp_f32_e32 v16, v16
	v_exp_f32_e32 v17, v17
	v_add_f32_e32 v16, 1.0, v16
	v_add_f32_e32 v17, 1.0, v17
	v_rcp_f32_e32 v16, v16
	v_rcp_f32_e32 v17, v17
	s_nop 0
	v_cvt_pk_bf16_f32 v17, v16, v17
	v_mul_f32_e32 v14, 0xbfb8aa3b, v14
	v_mul_f32_e32 v15, 0xbfb8aa3b, v15
	v_exp_f32_e32 v14, v14
	v_exp_f32_e32 v15, v15
	v_add_f32_e32 v14, 1.0, v14
	v_add_f32_e32 v15, 1.0, v15
	v_rcp_f32_e32 v14, v14
	v_rcp_f32_e32 v15, v15
	s_nop 0
	v_cvt_pk_bf16_f32 v16, v14, v15
	v_mul_f32_e32 v12, 0xbfb8aa3b, v12
	v_mul_f32_e32 v13, 0xbfb8aa3b, v13
	v_exp_f32_e32 v12, v12
	v_exp_f32_e32 v13, v13
	v_add_f32_e32 v12, 1.0, v12
	v_add_f32_e32 v13, 1.0, v13
	v_rcp_f32_e32 v12, v12
	v_rcp_f32_e32 v13, v13
	s_nop 0
	v_cvt_pk_bf16_f32 v15, v12, v13
	v_mul_f32_e32 v10, 0xbfb8aa3b, v10
	v_mul_f32_e32 v11, 0xbfb8aa3b, v11
	v_exp_f32_e32 v10, v10
	v_exp_f32_e32 v11, v11
	v_add_f32_e32 v10, 1.0, v10
	v_add_f32_e32 v11, 1.0, v11
	v_rcp_f32_e32 v10, v10
	v_rcp_f32_e32 v11, v11
	s_nop 0
	v_cvt_pk_bf16_f32 v14, v10, v11
	global_store_dwordx4 v[26:27], v[14:17], off offset:2048
	v_mul_f32_e32 v4, 0xbfb8aa3b, v4
	v_mul_f32_e32 v5, 0xbfb8aa3b, v5
	v_exp_f32_e32 v4, v4
	v_exp_f32_e32 v5, v5
	v_add_f32_e32 v4, 1.0, v4
	v_add_f32_e32 v5, 1.0, v5
	v_rcp_f32_e32 v4, v4
	v_rcp_f32_e32 v5, v5
	s_nop 0
	v_cvt_pk_bf16_f32 v5, v4, v5
	v_mul_f32_e32 v2, 0xbfb8aa3b, v2
	v_mul_f32_e32 v3, 0xbfb8aa3b, v3
	v_exp_f32_e32 v2, v2
	v_exp_f32_e32 v3, v3
	v_add_f32_e32 v2, 1.0, v2
	v_add_f32_e32 v3, 1.0, v3
	v_rcp_f32_e32 v2, v2
	v_rcp_f32_e32 v3, v3
	s_nop 0
	v_cvt_pk_bf16_f32 v4, v2, v3
	v_mul_f32_e32 v8, 0xbfb8aa3b, v8
	v_mul_f32_e32 v9, 0xbfb8aa3b, v9
	v_exp_f32_e32 v8, v8
	v_exp_f32_e32 v9, v9
	v_add_f32_e32 v8, 1.0, v8
	v_add_f32_e32 v9, 1.0, v9
	v_rcp_f32_e32 v8, v8
	v_rcp_f32_e32 v9, v9
	s_nop 0
	v_cvt_pk_bf16_f32 v3, v8, v9
	v_mul_f32_e32 v6, 0xbfb8aa3b, v6
	v_mul_f32_e32 v7, 0xbfb8aa3b, v7
	v_exp_f32_e32 v6, v6
	v_exp_f32_e32 v7, v7
	v_add_f32_e32 v6, 1.0, v6
	v_add_f32_e32 v7, 1.0, v7
	v_rcp_f32_e32 v6, v6
	v_rcp_f32_e32 v7, v7
	s_nop 0
	v_cvt_pk_bf16_f32 v2, v6, v7
	global_store_dwordx4 v[26:27], v[2:5], off offset:3072
	s_mov_b32 s100, 1
	s_branch .LBB0_234

.LBB0_993:
	s_and_b32 s10, s30, -4
	s_lshl_b32 s0, s7, 4
	s_and_b32 s3, s30, 3
	s_add_i32 s0, s0, s10
	s_or_b32 s0, s0, s3
	s_lshl_b32 s0, s0, 3
	s_add_i32 s0, s0, s27
	s_ashr_i32 s1, s0, 31
	s_lshl_b64 s[0:1], s[0:1], 14
	v_lshl_add_u64 v[66:67], v[206:207], 0, s[0:1]
	global_load_dwordx4 v[196:199], v[66:67], off
	global_load_dwordx4 v[192:195], v[66:67], off offset:1024
	global_load_dwordx4 v[188:191], v[66:67], off offset:2048
	global_load_dwordx4 v[184:187], v[66:67], off offset:3072
	v_add_co_u32_e32 v68, vcc, s63, v66
	s_movk_i32 s11, 0x2000
	s_nop 0
	v_addc_co_u32_e32 v69, vcc, 0, v67, vcc
	v_add_co_u32_e32 v78, vcc, s11, v66
	s_movk_i32 s11, 0x3000
	s_nop 0
	v_addc_co_u32_e32 v79, vcc, 0, v67, vcc
	global_load_dwordx4 v[180:183], v[78:79], off offset:-4096
	global_load_dwordx4 v[176:179], v[68:69], off offset:1024
	global_load_dwordx4 v[164:167], v[68:69], off offset:2048
	global_load_dwordx4 v[160:163], v[68:69], off offset:3072
	global_load_dwordx4 v[156:159], v[78:79], off
	global_load_dwordx4 v[138:141], v[78:79], off offset:1024
	global_load_dwordx4 v[126:129], v[78:79], off offset:2048
	global_load_dwordx4 v[114:117], v[78:79], off offset:3072
	v_add_co_u32_e32 v66, vcc, s11, v66
	s_lshl_b32 s1, s3, 3
	s_nop 0
	v_addc_co_u32_e32 v67, vcc, 0, v67, vcc
	global_load_dwordx4 v[102:105], v[66:67], off
	global_load_dwordx4 v[90:93], v[66:67], off offset:1024
	global_load_dwordx4 v[78:81], v[66:67], off offset:2048
	s_nop 0
	global_load_dwordx4 v[66:69], v[66:67], off offset:3072
	s_lshl_b32 s0, s7, 5
	s_add_i32 s1, s1, s27
	s_add_i32 s0, s1, s0
	s_ashr_i32 s1, s0, 31
	s_lshl_b64 s[0:1], s[0:1], 14
	s_cmp_lt_u32 s30, 4
	s_waitcnt vmcnt(0)
	v_lshlrev_b32_e32 v215, 16, v196
	v_and_b32_e32 v196, 0xffff0000, v196
	v_mov_b32_e32 v230, v215
	v_lshlrev_b32_e32 v215, 16, v198
	v_and_b32_e32 v198, 0xffff0000, v198
	v_mov_b32_e32 v231, v196
	v_lshlrev_b32_e32 v196, 16, v197
	v_mov_b32_e32 v233, v198
	v_lshlrev_b32_e32 v198, 16, v199
	v_and_b32_e32 v199, 0xffff0000, v199
	v_and_b32_e32 v197, 0xffff0000, v197
	v_pk_mul_f32 v[170:171], v[170:171], v[198:199]
	v_lshlrev_b32_e32 v198, 16, v194
	v_and_b32_e32 v194, 0xffff0000, v194
	v_mov_b32_e32 v199, v194
	v_pk_mul_f32 v[174:175], v[174:175], v[196:197]
	v_lshlrev_b32_e32 v196, 16, v192
	v_and_b32_e32 v192, 0xffff0000, v192
	v_lshlrev_b32_e32 v194, 16, v195
	v_and_b32_e32 v195, 0xffff0000, v195
	v_mov_b32_e32 v197, v192
	v_lshlrev_b32_e32 v192, 16, v193
	v_and_b32_e32 v193, 0xffff0000, v193
	v_pk_mul_f32 v[150:151], v[150:151], v[194:195]
	v_lshlrev_b32_e32 v194, 16, v190
	v_and_b32_e32 v190, 0xffff0000, v190
	v_mov_b32_e32 v195, v190
	v_pk_mul_f32 v[154:155], v[154:155], v[192:193]
	v_lshlrev_b32_e32 v192, 16, v188
	v_and_b32_e32 v188, 0xffff0000, v188
	v_lshlrev_b32_e32 v190, 16, v191
	v_and_b32_e32 v191, 0xffff0000, v191
	v_mov_b32_e32 v193, v188
	v_lshlrev_b32_e32 v188, 16, v189
	v_and_b32_e32 v189, 0xffff0000, v189
	v_pk_mul_f32 v[132:133], v[132:133], v[190:191]
	v_lshlrev_b32_e32 v190, 16, v186
	v_and_b32_e32 v186, 0xffff0000, v186
	v_mov_b32_e32 v191, v186
	v_pk_mul_f32 v[136:137], v[136:137], v[188:189]
	v_lshlrev_b32_e32 v188, 16, v184
	v_and_b32_e32 v184, 0xffff0000, v184
	v_lshlrev_b32_e32 v186, 16, v187
	v_and_b32_e32 v187, 0xffff0000, v187
	v_mov_b32_e32 v189, v184
	v_lshlrev_b32_e32 v184, 16, v185
	v_and_b32_e32 v185, 0xffff0000, v185
	v_pk_mul_f32 v[120:121], v[120:121], v[186:187]
	v_lshlrev_b32_e32 v186, 16, v182
	v_and_b32_e32 v182, 0xffff0000, v182
	v_mov_b32_e32 v187, v182
	v_pk_mul_f32 v[124:125], v[124:125], v[184:185]
	v_lshlrev_b32_e32 v184, 16, v180
	v_and_b32_e32 v180, 0xffff0000, v180
	v_lshlrev_b32_e32 v182, 16, v183
	v_and_b32_e32 v183, 0xffff0000, v183
	v_mov_b32_e32 v185, v180
	v_lshlrev_b32_e32 v180, 16, v181
	v_and_b32_e32 v181, 0xffff0000, v181
	v_pk_mul_f32 v[108:109], v[108:109], v[182:183]
	v_lshlrev_b32_e32 v182, 16, v178
	v_and_b32_e32 v178, 0xffff0000, v178
	v_mov_b32_e32 v183, v178
	v_pk_mul_f32 v[112:113], v[112:113], v[180:181]
	v_lshlrev_b32_e32 v180, 16, v176
	v_and_b32_e32 v176, 0xffff0000, v176
	v_lshlrev_b32_e32 v178, 16, v179
	v_and_b32_e32 v179, 0xffff0000, v179
	v_mov_b32_e32 v181, v176
	v_lshlrev_b32_e32 v176, 16, v177
	v_and_b32_e32 v177, 0xffff0000, v177
	v_pk_mul_f32 v[96:97], v[96:97], v[178:179]
	v_lshlrev_b32_e32 v178, 16, v166
	v_and_b32_e32 v166, 0xffff0000, v166
	v_mov_b32_e32 v179, v166
	v_pk_mul_f32 v[100:101], v[100:101], v[176:177]
	v_lshlrev_b32_e32 v176, 16, v164
	v_and_b32_e32 v164, 0xffff0000, v164
	v_lshlrev_b32_e32 v166, 16, v167
	v_and_b32_e32 v167, 0xffff0000, v167
	v_mov_b32_e32 v177, v164
	v_lshlrev_b32_e32 v164, 16, v165
	v_and_b32_e32 v165, 0xffff0000, v165
	v_pk_mul_f32 v[84:85], v[84:85], v[166:167]
	v_lshlrev_b32_e32 v166, 16, v162
	v_and_b32_e32 v162, 0xffff0000, v162
	v_mov_b32_e32 v167, v162
	v_pk_mul_f32 v[88:89], v[88:89], v[164:165]
	v_lshlrev_b32_e32 v164, 16, v160
	v_and_b32_e32 v160, 0xffff0000, v160
	v_lshlrev_b32_e32 v162, 16, v163
	v_and_b32_e32 v163, 0xffff0000, v163
	v_mov_b32_e32 v165, v160
	v_lshlrev_b32_e32 v160, 16, v161
	v_and_b32_e32 v161, 0xffff0000, v161
	v_pk_mul_f32 v[72:73], v[72:73], v[162:163]
	v_lshlrev_b32_e32 v162, 16, v158
	v_and_b32_e32 v158, 0xffff0000, v158
	v_mov_b32_e32 v163, v158
	v_pk_mul_f32 v[76:77], v[76:77], v[160:161]
	v_lshlrev_b32_e32 v160, 16, v156
	v_and_b32_e32 v156, 0xffff0000, v156
	v_lshlrev_b32_e32 v158, 16, v159
	v_and_b32_e32 v159, 0xffff0000, v159
	v_mov_b32_e32 v161, v156
	v_lshlrev_b32_e32 v156, 16, v157
	v_and_b32_e32 v157, 0xffff0000, v157
	v_pk_mul_f32 v[60:61], v[60:61], v[158:159]
	v_lshlrev_b32_e32 v158, 16, v140
	v_and_b32_e32 v140, 0xffff0000, v140
	v_mov_b32_e32 v159, v140
	v_pk_mul_f32 v[64:65], v[64:65], v[156:157]
	v_lshlrev_b32_e32 v156, 16, v138
	v_and_b32_e32 v138, 0xffff0000, v138
	v_lshlrev_b32_e32 v140, 16, v141
	v_and_b32_e32 v141, 0xffff0000, v141
	v_mov_b32_e32 v157, v138
	v_lshlrev_b32_e32 v138, 16, v139
	v_and_b32_e32 v139, 0xffff0000, v139
	v_pk_mul_f32 v[52:53], v[52:53], v[140:141]
	v_lshlrev_b32_e32 v140, 16, v128
	v_and_b32_e32 v128, 0xffff0000, v128
	v_pk_mul_f32 v[54:55], v[54:55], v[156:157]
	v_pk_mul_f32 v[56:57], v[56:57], v[138:139]
	v_lshlrev_b32_e32 v138, 16, v126
	v_and_b32_e32 v126, 0xffff0000, v126
	v_mov_b32_e32 v157, v128
	v_lshlrev_b32_e32 v128, 16, v129
	v_pk_mul_f32 v[50:51], v[50:51], v[158:159]
	v_mov_b32_e32 v139, v126
	v_lshlrev_b32_e32 v126, 16, v127
	v_and_b32_e32 v127, 0xffff0000, v127
	v_mov_b32_e32 v158, v128
	v_and_b32_e32 v128, 0xffff0000, v129
	v_mov_b32_e32 v156, v140
	v_mov_b32_e32 v159, v128
	v_pk_mul_f32 v[140:141], v[46:47], v[138:139]
	v_pk_mul_f32 v[128:129], v[48:49], v[126:127]
	v_pk_mul_f32 v[138:139], v[42:43], v[156:157]
	v_pk_mul_f32 v[126:127], v[44:45], v[158:159]
	v_lshlrev_b32_e32 v42, 16, v114
	v_and_b32_e32 v43, 0xffff0000, v114
	v_lshlrev_b32_e32 v44, 16, v115
	v_and_b32_e32 v45, 0xffff0000, v115
	v_lshlrev_b32_e32 v46, 16, v116
	v_and_b32_e32 v47, 0xffff0000, v116
	v_lshlrev_b32_e32 v48, 16, v117
	v_and_b32_e32 v49, 0xffff0000, v117
	v_pk_mul_f32 v[114:115], v[40:41], v[44:45]
	v_pk_mul_f32 v[156:157], v[38:39], v[42:43]
	v_pk_mul_f32 v[158:159], v[34:35], v[46:47]
	v_pk_mul_f32 v[116:117], v[36:37], v[48:49]
	v_lshlrev_b32_e32 v34, 16, v102
	v_and_b32_e32 v35, 0xffff0000, v102
	v_lshlrev_b32_e32 v36, 16, v103
	v_and_b32_e32 v37, 0xffff0000, v103
	v_lshlrev_b32_e32 v38, 16, v104
	v_and_b32_e32 v39, 0xffff0000, v104
	v_lshlrev_b32_e32 v40, 16, v105
	v_and_b32_e32 v41, 0xffff0000, v105
	v_pk_mul_f32 v[62:63], v[62:63], v[160:161]
	v_pk_mul_f32 v[58:59], v[58:59], v[162:163]
	v_pk_mul_f32 v[104:105], v[32:33], v[36:37]
	v_pk_mul_f32 v[162:163], v[30:31], v[34:35]
	v_pk_mul_f32 v[102:103], v[28:29], v[40:41]
	v_pk_mul_f32 v[160:161], v[26:27], v[38:39]
	v_lshlrev_b32_e32 v26, 16, v90
	v_and_b32_e32 v27, 0xffff0000, v90
	v_lshlrev_b32_e32 v28, 16, v91
	v_and_b32_e32 v29, 0xffff0000, v91
	v_lshlrev_b32_e32 v30, 16, v92
	v_and_b32_e32 v31, 0xffff0000, v92
	v_lshlrev_b32_e32 v32, 16, v93
	v_and_b32_e32 v33, 0xffff0000, v93
	v_pk_mul_f32 v[74:75], v[74:75], v[164:165]
	v_pk_mul_f32 v[70:71], v[70:71], v[166:167]
	v_pk_mul_f32 v[90:91], v[24:25], v[28:29]
	v_pk_mul_f32 v[164:165], v[22:23], v[26:27]
	v_pk_mul_f32 v[92:93], v[20:21], v[32:33]
	v_pk_mul_f32 v[166:167], v[18:19], v[30:31]
	v_lshlrev_b32_e32 v18, 16, v78
	v_and_b32_e32 v19, 0xffff0000, v78
	v_lshlrev_b32_e32 v20, 16, v79
	v_and_b32_e32 v21, 0xffff0000, v79
	v_lshlrev_b32_e32 v22, 16, v80
	v_and_b32_e32 v23, 0xffff0000, v80
	v_lshlrev_b32_e32 v24, 16, v81
	v_and_b32_e32 v25, 0xffff0000, v81
	v_pk_mul_f32 v[86:87], v[86:87], v[176:177]
	v_pk_mul_f32 v[82:83], v[82:83], v[178:179]
	v_pk_mul_f32 v[80:81], v[16:17], v[20:21]
	v_pk_mul_f32 v[178:179], v[14:15], v[18:19]
	v_pk_mul_f32 v[78:79], v[12:13], v[24:25]
	v_pk_mul_f32 v[176:177], v[10:11], v[22:23]
	v_lshlrev_b32_e32 v10, 16, v66
	v_and_b32_e32 v11, 0xffff0000, v66
	v_lshlrev_b32_e32 v12, 16, v67
	v_and_b32_e32 v13, 0xffff0000, v67
	v_lshlrev_b32_e32 v14, 16, v68
	v_and_b32_e32 v15, 0xffff0000, v68
	v_lshlrev_b32_e32 v16, 16, v69
	v_and_b32_e32 v17, 0xffff0000, v69
	v_mov_b32_e32 v232, v215
	v_pk_mul_f32 v[172:173], v[172:173], v[230:231]
	v_pk_mul_f32 v[168:169], v[168:169], v[232:233]
	v_pk_mul_f32 v[152:153], v[152:153], v[196:197]
	v_pk_mul_f32 v[148:149], v[148:149], v[198:199]
	v_pk_mul_f32 v[134:135], v[134:135], v[192:193]
	v_pk_mul_f32 v[130:131], v[130:131], v[194:195]
	v_pk_mul_f32 v[122:123], v[122:123], v[188:189]
	v_pk_mul_f32 v[118:119], v[118:119], v[190:191]
	v_pk_mul_f32 v[110:111], v[110:111], v[184:185]
	v_pk_mul_f32 v[106:107], v[106:107], v[186:187]
	v_pk_mul_f32 v[98:99], v[98:99], v[180:181]
	v_pk_mul_f32 v[94:95], v[94:95], v[182:183]
	v_pk_mul_f32 v[66:67], v[8:9], v[12:13]
	v_pk_mul_f32 v[180:181], v[6:7], v[10:11]
	v_pk_mul_f32 v[68:69], v[4:5], v[16:17]
	v_pk_mul_f32 v[182:183], v[2:3], v[14:15]
	v_lshl_add_u64 v[184:185], v[208:209], 0, s[0:1]
	s_cbranch_scc1 .LBB0_996
	global_load_dwordx4 v[186:189], v[184:185], off
	global_load_dwordx4 v[190:193], v[184:185], off offset:1024
	global_load_dwordx4 v[194:197], v[184:185], off offset:2048
	global_load_dwordx4 v[230:233], v[184:185], off offset:3072
	v_add_co_u32_e32 v2, vcc, s63, v184
	s_movk_i32 s0, 0x2000
	s_nop 0
	v_addc_co_u32_e32 v3, vcc, 0, v185, vcc
	v_add_co_u32_e32 v4, vcc, s0, v184
	s_movk_i32 s0, 0x3000
	s_nop 0
	v_addc_co_u32_e32 v5, vcc, 0, v185, vcc
	global_load_dwordx4 v[46:49], v[4:5], off offset:-4096
	global_load_dwordx4 v[42:45], v[2:3], off offset:1024
	global_load_dwordx4 v[38:41], v[2:3], off offset:2048
	global_load_dwordx4 v[34:37], v[2:3], off offset:3072
	global_load_dwordx4 v[30:33], v[4:5], off
	global_load_dwordx4 v[26:29], v[4:5], off offset:1024
	global_load_dwordx4 v[18:21], v[4:5], off offset:2048
	global_load_dwordx4 v[10:13], v[4:5], off offset:3072
	v_add_co_u32_e32 v2, vcc, s0, v184
	s_waitcnt vmcnt(0)
	v_lshlrev_b32_e32 v198, 16, v186
	v_addc_co_u32_e32 v3, vcc, 0, v185, vcc
	global_load_dwordx4 v[22:25], v[2:3], off
	global_load_dwordx4 v[14:17], v[2:3], off offset:1024
	global_load_dwordx4 v[6:9], v[2:3], off offset:2048
	s_nop 0
	global_load_dwordx4 v[2:5], v[2:3], off offset:3072
	v_and_b32_e32 v199, 0xffff0000, v186
	v_lshlrev_b32_e32 v186, 16, v187
	v_and_b32_e32 v187, 0xffff0000, v187
	v_pk_add_f32 v[174:175], v[174:175], v[186:187]
	v_lshlrev_b32_e32 v186, 16, v188
	v_and_b32_e32 v187, 0xffff0000, v188
	v_pk_add_f32 v[168:169], v[168:169], v[186:187]
	v_lshlrev_b32_e32 v186, 16, v189
	v_and_b32_e32 v187, 0xffff0000, v189
	v_pk_add_f32 v[170:171], v[170:171], v[186:187]
	v_lshlrev_b32_e32 v186, 16, v190
	v_and_b32_e32 v187, 0xffff0000, v190
	v_pk_add_f32 v[152:153], v[152:153], v[186:187]
	v_lshlrev_b32_e32 v186, 16, v191
	v_and_b32_e32 v187, 0xffff0000, v191
	v_pk_add_f32 v[154:155], v[154:155], v[186:187]
	v_lshlrev_b32_e32 v186, 16, v192
	v_and_b32_e32 v187, 0xffff0000, v192
	v_pk_add_f32 v[148:149], v[148:149], v[186:187]
	v_lshlrev_b32_e32 v186, 16, v193
	v_and_b32_e32 v187, 0xffff0000, v193
	v_pk_add_f32 v[150:151], v[150:151], v[186:187]
	v_lshlrev_b32_e32 v186, 16, v194
	v_and_b32_e32 v187, 0xffff0000, v194
	v_pk_add_f32 v[134:135], v[134:135], v[186:187]
	v_lshlrev_b32_e32 v186, 16, v195
	v_and_b32_e32 v187, 0xffff0000, v195
	v_pk_add_f32 v[136:137], v[136:137], v[186:187]
	v_lshlrev_b32_e32 v186, 16, v196
	v_and_b32_e32 v187, 0xffff0000, v196
	v_pk_add_f32 v[130:131], v[130:131], v[186:187]
	v_lshlrev_b32_e32 v186, 16, v197
	v_and_b32_e32 v187, 0xffff0000, v197
	v_pk_add_f32 v[132:133], v[132:133], v[186:187]
	v_lshlrev_b32_e32 v186, 16, v230
	v_and_b32_e32 v187, 0xffff0000, v230
	v_pk_add_f32 v[122:123], v[122:123], v[186:187]
	v_lshlrev_b32_e32 v186, 16, v231
	v_and_b32_e32 v187, 0xffff0000, v231
	v_pk_add_f32 v[124:125], v[124:125], v[186:187]
	v_lshlrev_b32_e32 v186, 16, v232
	v_and_b32_e32 v187, 0xffff0000, v232
	v_pk_add_f32 v[118:119], v[118:119], v[186:187]
	v_lshlrev_b32_e32 v186, 16, v233
	v_and_b32_e32 v187, 0xffff0000, v233
	v_pk_add_f32 v[120:121], v[120:121], v[186:187]
	v_lshlrev_b32_e32 v186, 16, v46
	v_and_b32_e32 v187, 0xffff0000, v46
	v_lshlrev_b32_e32 v46, 16, v47
	v_and_b32_e32 v47, 0xffff0000, v47
	v_pk_add_f32 v[112:113], v[112:113], v[46:47]
	v_lshlrev_b32_e32 v46, 16, v48
	v_and_b32_e32 v47, 0xffff0000, v48
	v_pk_add_f32 v[106:107], v[106:107], v[46:47]
	v_lshlrev_b32_e32 v46, 16, v49
	v_and_b32_e32 v47, 0xffff0000, v49
	v_pk_add_f32 v[108:109], v[108:109], v[46:47]
	v_lshlrev_b32_e32 v46, 16, v42
	v_and_b32_e32 v47, 0xffff0000, v42
	v_lshlrev_b32_e32 v42, 16, v43
	v_and_b32_e32 v43, 0xffff0000, v43
	v_pk_add_f32 v[100:101], v[100:101], v[42:43]
	v_lshlrev_b32_e32 v42, 16, v44
	v_and_b32_e32 v43, 0xffff0000, v44
	v_pk_add_f32 v[94:95], v[94:95], v[42:43]
	v_lshlrev_b32_e32 v42, 16, v45
	v_and_b32_e32 v43, 0xffff0000, v45
	v_pk_add_f32 v[96:97], v[96:97], v[42:43]
	v_lshlrev_b32_e32 v42, 16, v38
	v_and_b32_e32 v43, 0xffff0000, v38
	v_lshlrev_b32_e32 v38, 16, v39
	v_and_b32_e32 v39, 0xffff0000, v39
	v_pk_add_f32 v[88:89], v[88:89], v[38:39]
	v_lshlrev_b32_e32 v38, 16, v40
	v_and_b32_e32 v39, 0xffff0000, v40
	v_pk_add_f32 v[82:83], v[82:83], v[38:39]
	v_lshlrev_b32_e32 v38, 16, v41
	v_and_b32_e32 v39, 0xffff0000, v41
	v_pk_add_f32 v[84:85], v[84:85], v[38:39]
	v_lshlrev_b32_e32 v38, 16, v34
	v_and_b32_e32 v39, 0xffff0000, v34
	v_lshlrev_b32_e32 v34, 16, v35
	v_and_b32_e32 v35, 0xffff0000, v35
	v_pk_add_f32 v[76:77], v[76:77], v[34:35]
	v_lshlrev_b32_e32 v34, 16, v36
	v_and_b32_e32 v35, 0xffff0000, v36
	v_pk_add_f32 v[70:71], v[70:71], v[34:35]
	v_lshlrev_b32_e32 v34, 16, v37
	v_and_b32_e32 v35, 0xffff0000, v37
	v_pk_add_f32 v[72:73], v[72:73], v[34:35]
	v_lshlrev_b32_e32 v34, 16, v30
	v_and_b32_e32 v35, 0xffff0000, v30
	v_lshlrev_b32_e32 v30, 16, v31
	v_and_b32_e32 v31, 0xffff0000, v31
	v_pk_add_f32 v[64:65], v[64:65], v[30:31]
	v_lshlrev_b32_e32 v30, 16, v32
	v_and_b32_e32 v31, 0xffff0000, v32
	v_pk_add_f32 v[58:59], v[58:59], v[30:31]
	v_lshlrev_b32_e32 v30, 16, v33
	v_and_b32_e32 v31, 0xffff0000, v33
	v_pk_add_f32 v[60:61], v[60:61], v[30:31]
	v_lshlrev_b32_e32 v30, 16, v26
	v_and_b32_e32 v31, 0xffff0000, v26
	v_lshlrev_b32_e32 v26, 16, v27
	v_and_b32_e32 v27, 0xffff0000, v27
	v_pk_add_f32 v[56:57], v[56:57], v[26:27]
	v_lshlrev_b32_e32 v26, 16, v28
	v_and_b32_e32 v27, 0xffff0000, v28
	v_pk_add_f32 v[50:51], v[50:51], v[26:27]
	v_lshlrev_b32_e32 v26, 16, v29
	v_and_b32_e32 v27, 0xffff0000, v29
	v_pk_add_f32 v[52:53], v[52:53], v[26:27]
	v_lshlrev_b32_e32 v26, 16, v18
	v_and_b32_e32 v27, 0xffff0000, v18
	v_lshlrev_b32_e32 v18, 16, v19
	v_and_b32_e32 v19, 0xffff0000, v19
	v_pk_add_f32 v[128:129], v[128:129], v[18:19]
	v_lshlrev_b32_e32 v18, 16, v20
	v_and_b32_e32 v19, 0xffff0000, v20
	v_pk_add_f32 v[138:139], v[138:139], v[18:19]
	v_lshlrev_b32_e32 v18, 16, v21
	v_and_b32_e32 v19, 0xffff0000, v21
	v_pk_add_f32 v[126:127], v[126:127], v[18:19]
	v_lshlrev_b32_e32 v18, 16, v10
	v_and_b32_e32 v19, 0xffff0000, v10
	v_lshlrev_b32_e32 v10, 16, v11
	v_and_b32_e32 v11, 0xffff0000, v11
	v_pk_add_f32 v[114:115], v[114:115], v[10:11]
	v_lshlrev_b32_e32 v10, 16, v12
	v_and_b32_e32 v11, 0xffff0000, v12
	v_pk_add_f32 v[158:159], v[158:159], v[10:11]
	v_lshlrev_b32_e32 v10, 16, v13
	v_and_b32_e32 v11, 0xffff0000, v13
	v_pk_add_f32 v[116:117], v[116:117], v[10:11]
	s_waitcnt vmcnt(0)
	v_lshlrev_b32_e32 v10, 16, v22
	v_and_b32_e32 v11, 0xffff0000, v22
	v_pk_add_f32 v[162:163], v[162:163], v[10:11]
	v_lshlrev_b32_e32 v10, 16, v23
	v_and_b32_e32 v11, 0xffff0000, v23
	v_pk_add_f32 v[104:105], v[104:105], v[10:11]
	v_lshlrev_b32_e32 v10, 16, v24
	v_and_b32_e32 v11, 0xffff0000, v24
	v_pk_add_f32 v[160:161], v[160:161], v[10:11]
	v_lshlrev_b32_e32 v10, 16, v25
	v_and_b32_e32 v11, 0xffff0000, v25
	v_pk_add_f32 v[102:103], v[102:103], v[10:11]
	v_lshlrev_b32_e32 v10, 16, v14
	v_and_b32_e32 v11, 0xffff0000, v14
	v_pk_add_f32 v[164:165], v[164:165], v[10:11]
	v_lshlrev_b32_e32 v10, 16, v15
	v_and_b32_e32 v11, 0xffff0000, v15
	v_pk_add_f32 v[90:91], v[90:91], v[10:11]
	v_lshlrev_b32_e32 v10, 16, v16
	v_and_b32_e32 v11, 0xffff0000, v16
	v_pk_add_f32 v[166:167], v[166:167], v[10:11]
	v_lshlrev_b32_e32 v10, 16, v17
	v_and_b32_e32 v11, 0xffff0000, v17
	v_pk_add_f32 v[92:93], v[92:93], v[10:11]
	v_lshlrev_b32_e32 v10, 16, v6
	v_and_b32_e32 v11, 0xffff0000, v6
	v_lshlrev_b32_e32 v6, 16, v7
	v_and_b32_e32 v7, 0xffff0000, v7
	v_pk_add_f32 v[80:81], v[80:81], v[6:7]
	v_lshlrev_b32_e32 v6, 16, v8
	v_and_b32_e32 v7, 0xffff0000, v8
	v_pk_add_f32 v[176:177], v[176:177], v[6:7]
	v_lshlrev_b32_e32 v6, 16, v9
	v_and_b32_e32 v7, 0xffff0000, v9
	v_pk_add_f32 v[78:79], v[78:79], v[6:7]
	v_lshlrev_b32_e32 v6, 16, v2
	v_and_b32_e32 v7, 0xffff0000, v2
	v_lshlrev_b32_e32 v2, 16, v3
	v_and_b32_e32 v3, 0xffff0000, v3
	v_pk_add_f32 v[66:67], v[66:67], v[2:3]
	v_lshlrev_b32_e32 v2, 16, v4
	v_and_b32_e32 v3, 0xffff0000, v4
	v_pk_add_f32 v[182:183], v[182:183], v[2:3]
	v_lshlrev_b32_e32 v2, 16, v5
	v_and_b32_e32 v3, 0xffff0000, v5
	v_pk_add_f32 v[172:173], v[172:173], v[198:199]
	v_pk_add_f32 v[110:111], v[110:111], v[186:187]
	v_pk_add_f32 v[98:99], v[98:99], v[46:47]
	v_pk_add_f32 v[86:87], v[86:87], v[42:43]
	v_pk_add_f32 v[74:75], v[74:75], v[38:39]
	v_pk_add_f32 v[62:63], v[62:63], v[34:35]
	v_pk_add_f32 v[54:55], v[54:55], v[30:31]
	v_pk_add_f32 v[140:141], v[140:141], v[26:27]
	v_pk_add_f32 v[156:157], v[156:157], v[18:19]
	v_pk_add_f32 v[178:179], v[178:179], v[10:11]
	v_pk_add_f32 v[180:181], v[180:181], v[6:7]
	v_pk_add_f32 v[68:69], v[68:69], v[2:3]
	s_cmp_eq_u32 s10, 12
	s_mov_b64 s[0:1], -1
	s_cbranch_scc0 .LBB0_997
